# v25 + nt hint on the final f32 output stores of the last-layer FFN-down epilogue
# speedup vs baseline: 1.0205x; 1.0205x over previous
.LBB0_1416:
	s_cmp_lt_i32 s43, 32
	v_lshl_add_u32 v164, s43, 8, v154
	v_lshl_or_b32 v162, s44, 8, v156
	s_cselect_b32 s2, s87, 0x6000
	s_cselect_b32 s22, s68, s96
	s_cselect_b32 s23, s69, s97
	s_cmp_gt_i32 s43, 15
	v_ashrrev_i32_e32 v165, 31, v164
	s_cselect_b32 s2, s2, 0
	v_ashrrev_i32_e32 v163, 31, v162
	v_lshlrev_b64 v[132:133], 11, v[164:165]
	s_lshl_b32 s2, s2, 2
	v_lshl_add_u64 v[132:133], v[132:133], 0, v[162:163]
	s_add_u32 s2, s49, s2
	v_lshlrev_b64 v[152:153], 2, v[132:133]
	s_addc_u32 s3, s50, 0
	v_lshl_add_u64 v[166:167], s[96:97], 0, v[152:153]
	v_lshl_add_u64 v[130:131], v[162:163], 2, s[2:3]
	global_load_dwordx4 v[142:145], v[130:131], off
	global_load_dwordx4 v[138:141], v[130:131], off offset:64
	global_load_dwordx4 v[134:137], v[130:131], off offset:512
	global_load_dwordx4 v[130:133], v[130:131], off offset:576
	v_lshl_add_u64 v[168:169], s[22:23], 0, v[152:153]
	s_and_b64 vcc, exec, s[0:1]
	s_mov_b64 s[0:1], -1
	v_mov_b64_e32 v[240:241], v[166:167]
	global_load_dwordx4 v[220:223], v[240:241], off
	global_load_dwordx4 v[224:227], v[240:241], off offset:64
	global_load_dwordx4 v[228:231], v[240:241], off offset:512
	global_load_dwordx4 v[232:235], v[240:241], off offset:576
	s_mov_b64 s[2:3], 0x20000
	v_lshl_add_u64 v[240:241], v[166:167], 0, s[2:3]
	global_load_dwordx4 v[236:239], v[240:241], off
	global_load_dwordx4 v[170:173], v[240:241], off offset:64
	global_load_dwordx4 v[174:177], v[240:241], off offset:512
	global_load_dwordx4 v[178:181], v[240:241], off offset:576
	s_mov_b64 s[2:3], 0x40000
	v_lshl_add_u64 v[240:241], v[166:167], 0, s[2:3]
	global_load_dwordx4 v[182:185], v[240:241], off
	global_load_dwordx4 v[186:189], v[240:241], off offset:64
	global_load_dwordx4 v[190:193], v[240:241], off offset:512
	global_load_dwordx4 v[202:205], v[240:241], off offset:576
	s_mov_b64 s[2:3], 0x60000
	v_lshl_add_u64 v[240:241], v[166:167], 0, s[2:3]
	global_load_dwordx4 v[206:209], v[240:241], off
	global_load_dwordx4 v[214:217], v[240:241], off offset:64
	global_load_dwordx4 v[158:161], v[240:241], off offset:512
	s_waitcnt vmcnt(14)
	v_pk_fma_f32 v[222:223], v[128:129], v[144:145], v[222:223]
	v_pk_fma_f32 v[220:221], v[126:127], v[142:143], v[220:221]
	v_mov_b64_e32 v[242:243], v[168:169]
	global_store_dwordx4 v[242:243], v[220:223], off nt
	s_nop 1
	global_load_dwordx4 v[220:223], v[240:241], off offset:576
	s_waitcnt vmcnt(15)
	v_pk_fma_f32 v[226:227], v[124:125], v[140:141], v[226:227]
	v_pk_fma_f32 v[224:225], v[122:123], v[138:139], v[224:225]
	global_store_dwordx4 v[242:243], v[224:227], off offset:64 nt
	s_mov_b64 s[2:3], 0x100000
	v_lshl_add_u64 v[240:241], v[166:167], 0, s[2:3]
	global_load_dwordx4 v[224:227], v[240:241], off
	s_waitcnt vmcnt(16)
	v_pk_fma_f32 v[230:231], v[120:121], v[136:137], v[230:231]
	v_pk_fma_f32 v[228:229], v[118:119], v[134:135], v[228:229]
	global_store_dwordx4 v[242:243], v[228:231], off offset:512 nt
	s_nop 1
	global_load_dwordx4 v[228:231], v[240:241], off offset:64
	s_waitcnt vmcnt(17)
	v_pk_fma_f32 v[234:235], v[108:109], v[132:133], v[234:235]
	v_pk_fma_f32 v[232:233], v[106:107], v[130:131], v[232:233]
	global_store_dwordx4 v[242:243], v[232:235], off offset:576 nt
	s_nop 1
	global_load_dwordx4 v[232:235], v[240:241], off offset:512
	s_waitcnt vmcnt(18)
	v_pk_fma_f32 v[238:239], v[116:117], v[144:145], v[238:239]
	v_pk_fma_f32 v[236:237], v[114:115], v[142:143], v[236:237]
	s_mov_b64 s[2:3], 0x20000
	v_lshl_add_u64 v[242:243], v[168:169], 0, s[2:3]
	global_store_dwordx4 v[242:243], v[236:239], off nt
	s_nop 1
	global_load_dwordx4 v[236:239], v[240:241], off offset:576
	s_waitcnt vmcnt(19)
	v_pk_fma_f32 v[172:173], v[112:113], v[140:141], v[172:173]
	v_pk_fma_f32 v[170:171], v[110:111], v[138:139], v[170:171]
	global_store_dwordx4 v[242:243], v[170:173], off offset:64 nt
	s_mov_b64 s[2:3], 0x120000
	v_lshl_add_u64 v[240:241], v[166:167], 0, s[2:3]
	global_load_dwordx4 v[170:173], v[240:241], off
	s_waitcnt vmcnt(20)
	v_pk_fma_f32 v[176:177], v[104:105], v[136:137], v[176:177]
	v_pk_fma_f32 v[174:175], v[102:103], v[134:135], v[174:175]
	global_store_dwordx4 v[242:243], v[174:177], off offset:512 nt
	s_nop 1
	global_load_dwordx4 v[174:177], v[240:241], off offset:64
	s_waitcnt vmcnt(21)
	v_pk_fma_f32 v[180:181], v[90:91], v[132:133], v[180:181]
	v_pk_fma_f32 v[178:179], v[88:89], v[130:131], v[178:179]
	global_store_dwordx4 v[242:243], v[178:181], off offset:576 nt
	s_nop 1
	global_load_dwordx4 v[178:181], v[240:241], off offset:512
	s_waitcnt vmcnt(22)
	v_pk_fma_f32 v[184:185], v[100:101], v[144:145], v[184:185]
	v_pk_fma_f32 v[182:183], v[98:99], v[142:143], v[182:183]
	s_mov_b64 s[2:3], 0x40000
	v_lshl_add_u64 v[242:243], v[168:169], 0, s[2:3]
	global_store_dwordx4 v[242:243], v[182:185], off nt
	s_nop 1
	global_load_dwordx4 v[182:185], v[240:241], off offset:576
	s_waitcnt vmcnt(23)
	v_pk_fma_f32 v[188:189], v[94:95], v[140:141], v[188:189]
	v_pk_fma_f32 v[186:187], v[92:93], v[138:139], v[186:187]
	global_store_dwordx4 v[242:243], v[186:189], off offset:64 nt
	s_mov_b64 s[2:3], 0x140000
	v_lshl_add_u64 v[240:241], v[166:167], 0, s[2:3]
	global_load_dwordx4 v[186:189], v[240:241], off
	s_waitcnt vmcnt(24)
	v_pk_fma_f32 v[192:193], v[86:87], v[136:137], v[192:193]
	v_pk_fma_f32 v[190:191], v[84:85], v[134:135], v[190:191]
	global_store_dwordx4 v[242:243], v[190:193], off offset:512 nt
	s_nop 1
	global_load_dwordx4 v[190:193], v[240:241], off offset:64
	s_waitcnt vmcnt(25)
	v_pk_fma_f32 v[204:205], v[74:75], v[132:133], v[204:205]
	v_pk_fma_f32 v[202:203], v[72:73], v[130:131], v[202:203]
	global_store_dwordx4 v[242:243], v[202:205], off offset:576 nt
	s_nop 1
	global_load_dwordx4 v[202:205], v[240:241], off offset:512
	s_waitcnt vmcnt(26)
	v_pk_fma_f32 v[208:209], v[82:83], v[144:145], v[208:209]
	v_pk_fma_f32 v[206:207], v[80:81], v[142:143], v[206:207]
	s_mov_b64 s[2:3], 0x60000
	v_lshl_add_u64 v[242:243], v[168:169], 0, s[2:3]
	global_store_dwordx4 v[242:243], v[206:209], off nt
	s_nop 1
	global_load_dwordx4 v[206:209], v[240:241], off offset:576
	s_waitcnt vmcnt(27)
	v_pk_fma_f32 v[216:217], v[78:79], v[140:141], v[216:217]
	v_pk_fma_f32 v[214:215], v[76:77], v[138:139], v[214:215]
	global_store_dwordx4 v[242:243], v[214:217], off offset:64 nt
	s_mov_b64 s[2:3], 0x160000
	v_lshl_add_u64 v[240:241], v[166:167], 0, s[2:3]
	global_load_dwordx4 v[214:217], v[240:241], off
	s_waitcnt vmcnt(28)
	v_pk_fma_f32 v[160:161], v[70:71], v[136:137], v[160:161]
	v_pk_fma_f32 v[158:159], v[68:69], v[134:135], v[158:159]
	global_store_dwordx4 v[242:243], v[158:161], off offset:512 nt
	s_nop 1
	global_load_dwordx4 v[158:161], v[240:241], off offset:64
	s_waitcnt vmcnt(28)
	v_pk_fma_f32 v[222:223], v[66:67], v[132:133], v[222:223]
	v_pk_fma_f32 v[220:221], v[64:65], v[130:131], v[220:221]
	global_store_dwordx4 v[242:243], v[220:223], off offset:576 nt
	s_nop 1
	global_load_dwordx4 v[220:223], v[240:241], off offset:512
	s_waitcnt vmcnt(28)
	v_pk_fma_f32 v[226:227], v[62:63], v[144:145], v[226:227]
	v_pk_fma_f32 v[224:225], v[60:61], v[142:143], v[224:225]
	s_mov_b64 s[2:3], 0x100000
	v_lshl_add_u64 v[242:243], v[168:169], 0, s[2:3]
	global_store_dwordx4 v[242:243], v[224:227], off nt
	s_nop 1
	global_load_dwordx4 v[224:227], v[240:241], off offset:576
	s_waitcnt vmcnt(28)
	v_pk_fma_f32 v[230:231], v[58:59], v[140:141], v[230:231]
	v_pk_fma_f32 v[228:229], v[56:57], v[138:139], v[228:229]
	global_store_dwordx4 v[242:243], v[228:231], off offset:64 nt
	s_waitcnt vmcnt(27)
	v_pk_fma_f32 v[234:235], v[54:55], v[136:137], v[234:235]
	v_pk_fma_f32 v[232:233], v[52:53], v[134:135], v[232:233]
	global_store_dwordx4 v[242:243], v[232:235], off offset:512 nt
	s_waitcnt vmcnt(26)
	v_pk_fma_f32 v[238:239], v[42:43], v[132:133], v[238:239]
	v_pk_fma_f32 v[236:237], v[40:41], v[130:131], v[236:237]
	global_store_dwordx4 v[242:243], v[236:239], off offset:576 nt
	s_waitcnt vmcnt(25)
	v_pk_fma_f32 v[172:173], v[50:51], v[144:145], v[172:173]
	v_pk_fma_f32 v[170:171], v[48:49], v[142:143], v[170:171]
	s_mov_b64 s[2:3], 0x120000
	v_lshl_add_u64 v[242:243], v[168:169], 0, s[2:3]
	global_store_dwordx4 v[242:243], v[170:173], off nt
	s_waitcnt vmcnt(24)
	v_pk_fma_f32 v[176:177], v[46:47], v[140:141], v[176:177]
	v_pk_fma_f32 v[174:175], v[44:45], v[138:139], v[174:175]
	global_store_dwordx4 v[242:243], v[174:177], off offset:64 nt
	s_waitcnt vmcnt(23)
	v_pk_fma_f32 v[180:181], v[38:39], v[136:137], v[180:181]
	v_pk_fma_f32 v[178:179], v[36:37], v[134:135], v[178:179]
	global_store_dwordx4 v[242:243], v[178:181], off offset:512 nt
	s_waitcnt vmcnt(22)
	v_pk_fma_f32 v[184:185], v[26:27], v[132:133], v[184:185]
	v_pk_fma_f32 v[182:183], v[24:25], v[130:131], v[182:183]
	global_store_dwordx4 v[242:243], v[182:185], off offset:576 nt
	s_waitcnt vmcnt(21)
	v_pk_fma_f32 v[188:189], v[34:35], v[144:145], v[188:189]
	v_pk_fma_f32 v[186:187], v[32:33], v[142:143], v[186:187]
	s_mov_b64 s[2:3], 0x140000
	v_lshl_add_u64 v[242:243], v[168:169], 0, s[2:3]
	global_store_dwordx4 v[242:243], v[186:189], off nt
	s_waitcnt vmcnt(20)
	v_pk_fma_f32 v[192:193], v[30:31], v[140:141], v[192:193]
	v_pk_fma_f32 v[190:191], v[28:29], v[138:139], v[190:191]
	global_store_dwordx4 v[242:243], v[190:193], off offset:64 nt
	s_waitcnt vmcnt(19)
	v_pk_fma_f32 v[204:205], v[22:23], v[136:137], v[204:205]
	v_pk_fma_f32 v[202:203], v[20:21], v[134:135], v[202:203]
	global_store_dwordx4 v[242:243], v[202:205], off offset:512 nt
	s_waitcnt vmcnt(18)
	v_pk_fma_f32 v[208:209], v[10:11], v[132:133], v[208:209]
	v_pk_fma_f32 v[206:207], v[8:9], v[130:131], v[206:207]
	global_store_dwordx4 v[242:243], v[206:209], off offset:576 nt
	s_waitcnt vmcnt(17)
	v_pk_fma_f32 v[216:217], v[18:19], v[144:145], v[216:217]
	v_pk_fma_f32 v[214:215], v[16:17], v[142:143], v[214:215]
	s_mov_b64 s[2:3], 0x160000
	v_lshl_add_u64 v[242:243], v[168:169], 0, s[2:3]
	global_store_dwordx4 v[242:243], v[214:217], off nt
	s_waitcnt vmcnt(16)
	v_pk_fma_f32 v[160:161], v[14:15], v[140:141], v[160:161]
	v_pk_fma_f32 v[158:159], v[12:13], v[138:139], v[158:159]
	global_store_dwordx4 v[242:243], v[158:161], off offset:64 nt
	s_waitcnt vmcnt(15)
	v_pk_fma_f32 v[222:223], v[6:7], v[136:137], v[222:223]
	v_pk_fma_f32 v[220:221], v[4:5], v[134:135], v[220:221]
	global_store_dwordx4 v[242:243], v[220:223], off offset:512 nt
	s_waitcnt vmcnt(14)
	v_pk_fma_f32 v[226:227], v[2:3], v[132:133], v[226:227]
	v_pk_fma_f32 v[224:225], v[0:1], v[130:131], v[224:225]
	global_store_dwordx4 v[242:243], v[224:227], off offset:576 nt
	s_mov_b64 s[2:3], 0x160000
	s_cbranch_vccnz .LBB0_1401
	s_andn2_b64 vcc, exec, s[8:9]
	s_cbranch_vccnz .LBB0_1400
	s_barrier
	s_branch .LBB0_1400
